# WA table loads hoisted + FF1 a_ready hook loads issued one K-iteration early (no vmcnt(0) drain in the K-loop), on top of v22
# baseline (speedup 1.0000x reference)
; __device__ __forceinline__ unsigned pk2(float lo, float hi) { return pg8::cvt_pk_bf16(lo, hi); }
; __device__ __forceinline__ void ssm_tables(unsigned char* ws, int l, const int tid) {
;     ...
;     for (int it = gt; it < NG * 2 * NS * LCH; it += NGT) { const int i = it & 63, n = (it >> 6) & 63, dir = (it >> 12) & 1, g = it >> 13;
;         const int pb = (g * 2 + dir) * NS + n; const f32x2 pw = ptab[(size_t)pb * 65 + (dir ? i : 63 - i)];
;         unsigned re[8], im[8];
; #pragma unroll
;         for (int q = 0; q < 16; q += 2) { const f32x2 b0 = bbar[(size_t)pb * NP + q], b1 = bbar[(size_t)pb * NP + q + 1];
;             re[q >> 1] = pk2(pw.x * b0.x - pw.y * b0.y, pw.x * b1.x - pw.y * b1.y); im[q >> 1] = pk2(pw.x * b0.y + pw.y * b0.x, pw.x * b1.y + pw.y * b1.x); }
;         bf16* r0 = WA + ((size_t)(g * 256 + dir * 128 + 2 * n) * 1024 + i * 16);
;         *(u32x4*)(r0) = (u32x4){re[0], re[1], re[2], re[3]}; *(u32x4*)(r0 + 8) = (u32x4){re[4], re[5], re[6], re[7]};
;         *(u32x4*)(r0 + 1024) = (u32x4){im[0], im[1], im[2], im[3]}; *(u32x4*)(r0 + 1024 + 8) = (u32x4){im[4], im[5], im[6], im[7]}; }
.LBB0_270:
	v_bfe_u32 v35, v9, 12, 1
	v_ashrrev_i32_e32 v36, 13, v9
	v_bfe_u32 v34, v9, 6, 6
	s_waitcnt vmcnt(5)
	v_lshlrev_b32_e32 v10, 7, v36
	v_lshlrev_b32_e32 v11, 6, v35
	v_cmp_eq_u32_e32 vcc, 0, v35
	v_or3_b32 v10, v11, v10, v34
	v_ashrrev_i32_e32 v11, 31, v10
	v_cndmask_b32_e32 v12, v7, v8, vcc
	v_lshlrev_b32_e32 v184, 3, v12
	v_mad_i64_i32 v[12:13], s[14:15], v10, s44, v[2:3]
	v_lshl_add_u64 v[12:13], v[12:13], 0, v[184:185]
	v_lshlrev_b64 v[10:11], 7, v[10:11]
	v_lshl_add_u64 v[28:29], s[36:37], 0, v[10:11]
	global_load_dwordx2 v[30:31], v[12:13], off
	s_nop 0
	global_load_dwordx4 v[100:103], v[28:29], off
	global_load_dwordx4 v[104:107], v[28:29], off offset:16
	global_load_dwordx4 v[108:111], v[28:29], off offset:32
	global_load_dwordx4 v[112:115], v[28:29], off offset:48
	global_load_dwordx4 v[116:119], v[28:29], off offset:64
	global_load_dwordx4 v[120:123], v[28:29], off offset:80
	global_load_dwordx4 v[124:127], v[28:29], off offset:96
	global_load_dwordx4 v[128:131], v[28:29], off offset:112
	v_add_u32_e32 v9, s6, v9
	s_mov_b32 s3, 0x3ffff
	v_cmp_lt_i32_e32 vcc, s3, v9
	s_or_b64 s[38:39], vcc, s[38:39]
	s_waitcnt vmcnt(0)
	v_pk_mul_f32 v[14:15], v[30:31], v[100:101]
	v_pk_mul_f32 v[16:17], v[30:31], v[102:103]
	v_pk_mul_f32 v[10:11], v[30:31], v[100:101] op_sel:[0,1] op_sel_hi:[1,0]
	v_pk_mul_f32 v[12:13], v[30:31], v[102:103] op_sel:[0,1] op_sel_hi:[1,0]
	v_sub_f32_e32 v14, v14, v15
	v_sub_f32_e32 v15, v16, v17
	v_add_f32_e32 v11, v10, v11
	v_add_f32_e32 v12, v12, v13
	v_cvt_pk_bf16_f32 v10, v14, v15
	v_cvt_pk_bf16_f32 v14, v11, v12
	s_waitcnt vmcnt(0)
	v_pk_mul_f32 v[12:13], v[30:31], v[104:105]
	v_pk_mul_f32 v[20:21], v[30:31], v[106:107]
	v_pk_mul_f32 v[18:19], v[30:31], v[106:107] op_sel:[0,1] op_sel_hi:[1,0]
	v_pk_mul_f32 v[16:17], v[30:31], v[104:105] op_sel:[0,1] op_sel_hi:[1,0]
	v_sub_f32_e32 v11, v12, v13
	v_add_f32_e32 v15, v18, v19
	v_sub_f32_e32 v12, v20, v21
	v_add_f32_e32 v13, v16, v17
	v_cvt_pk_bf16_f32 v11, v11, v12
	v_cvt_pk_bf16_f32 v15, v13, v15
	s_waitcnt vmcnt(0)
	v_pk_mul_f32 v[12:13], v[30:31], v[108:109]
	v_pk_mul_f32 v[16:17], v[30:31], v[108:109] op_sel:[0,1] op_sel_hi:[1,0]
	v_pk_mul_f32 v[20:21], v[30:31], v[110:111]
	v_pk_mul_f32 v[18:19], v[30:31], v[110:111] op_sel:[0,1] op_sel_hi:[1,0]
	v_sub_f32_e32 v12, v12, v13
	v_add_f32_e32 v16, v16, v17
	v_sub_f32_e32 v13, v20, v21
	v_add_f32_e32 v17, v18, v19
	v_cvt_pk_bf16_f32 v12, v12, v13
	v_cvt_pk_bf16_f32 v16, v16, v17
	s_waitcnt vmcnt(0)
	v_pk_mul_f32 v[22:23], v[30:31], v[112:113]
	v_pk_mul_f32 v[24:25], v[30:31], v[114:115]
	v_pk_mul_f32 v[18:19], v[30:31], v[112:113] op_sel:[0,1] op_sel_hi:[1,0]
	v_pk_mul_f32 v[20:21], v[30:31], v[114:115] op_sel:[0,1] op_sel_hi:[1,0]
	v_sub_f32_e32 v13, v22, v23
	v_sub_f32_e32 v17, v24, v25
	v_add_f32_e32 v18, v18, v19
	v_add_f32_e32 v19, v20, v21
	v_cvt_pk_bf16_f32 v13, v13, v17
	v_cvt_pk_bf16_f32 v17, v18, v19
	s_waitcnt vmcnt(0)
	v_pk_mul_f32 v[22:23], v[30:31], v[116:117]
	v_pk_mul_f32 v[24:25], v[30:31], v[118:119]
	v_pk_mul_f32 v[18:19], v[30:31], v[116:117] op_sel:[0,1] op_sel_hi:[1,0]
	v_pk_mul_f32 v[20:21], v[30:31], v[118:119] op_sel:[0,1] op_sel_hi:[1,0]
	v_sub_f32_e32 v22, v22, v23
	v_sub_f32_e32 v23, v24, v25
	v_add_f32_e32 v19, v18, v19
	v_add_f32_e32 v20, v20, v21
	v_cvt_pk_bf16_f32 v18, v22, v23
	v_cvt_pk_bf16_f32 v22, v19, v20
	s_waitcnt vmcnt(0)
	v_pk_mul_f32 v[20:21], v[30:31], v[120:121]
	v_pk_mul_f32 v[32:33], v[30:31], v[122:123]
	v_pk_mul_f32 v[26:27], v[30:31], v[122:123] op_sel:[0,1] op_sel_hi:[1,0]
	v_pk_mul_f32 v[24:25], v[30:31], v[120:121] op_sel:[0,1] op_sel_hi:[1,0]
	v_sub_f32_e32 v19, v20, v21
	v_add_f32_e32 v23, v26, v27
	v_sub_f32_e32 v20, v32, v33
	v_add_f32_e32 v21, v24, v25
	v_cvt_pk_bf16_f32 v19, v19, v20
	v_cvt_pk_bf16_f32 v23, v21, v23
	s_waitcnt vmcnt(0)
	v_pk_mul_f32 v[20:21], v[30:31], v[124:125]
	v_pk_mul_f32 v[24:25], v[30:31], v[124:125] op_sel:[0,1] op_sel_hi:[1,0]
	v_pk_mul_f32 v[32:33], v[30:31], v[126:127]
	v_pk_mul_f32 v[26:27], v[30:31], v[126:127] op_sel:[0,1] op_sel_hi:[1,0]
	v_sub_f32_e32 v20, v20, v21
	v_add_f32_e32 v24, v24, v25
	v_sub_f32_e32 v21, v32, v33
	v_add_f32_e32 v25, v26, v27
	v_cvt_pk_bf16_f32 v20, v20, v21
	v_cvt_pk_bf16_f32 v24, v24, v25
	v_lshlrev_b32_e32 v21, 8, v36
	v_lshlrev_b32_e32 v25, 7, v35
	v_lshlrev_b32_e32 v32, 1, v34
	v_or3_b32 v32, v25, v21, v32
	v_ashrrev_i32_e32 v33, 31, v32
	v_lshlrev_b64 v[32:33], 11, v[32:33]
	v_lshl_add_u64 v[32:33], v[0:1], 0, v[32:33]
	s_waitcnt vmcnt(0)
	v_pk_mul_f32 v[34:35], v[30:31], v[128:129]
	v_pk_mul_f32 v[36:37], v[30:31], v[130:131]
	v_pk_mul_f32 v[26:27], v[30:31], v[128:129] op_sel:[0,1] op_sel_hi:[1,0]
	v_pk_mul_f32 v[28:29], v[30:31], v[130:131] op_sel:[0,1] op_sel_hi:[1,0]
	v_sub_f32_e32 v21, v34, v35
	v_sub_f32_e32 v25, v36, v37
	v_add_f32_e32 v26, v26, v27
	v_add_f32_e32 v27, v28, v29
	v_cvt_pk_bf16_f32 v21, v21, v25
	v_cvt_pk_bf16_f32 v25, v26, v27
	global_store_dwordx4 v[32:33], v[10:13], off
	global_store_dwordx4 v[32:33], v[14:17], off offset:2048
	global_store_dwordx4 v[32:33], v[18:21], off offset:16
	global_store_dwordx4 v[32:33], v[22:25], off offset:2064
	s_andn2_b64 exec, exec, s[38:39]
	s_cbranch_execnz .LBB0_270

; #define LAS __attribute__((address_space(3)))
; __device__ __forceinline__ int lane_id_asm() { int l; asm volatile("v_mbcnt_lo_u32_b32 %0, -1, 0\n\tv_mbcnt_hi_u32_b32 %0, -1, %0" : "=v"(l)); return l; }
; __device__ __forceinline__ float sum16(const float* p) { const f32x4* q = (const f32x4*)p; return hsum4((q[0] + q[1]) + (q[2] + q[3])); }
;     __device__ __forceinline__ float table_val(int pm, int, int t) const { return t < 256 ? rsqrtf(sum16(px + (size_t)(pm * 256 + t) * 16) * (1.f / 1024.f) + EPS) : 0.f; }
;     __device__ __forceinline__ float table_val(int pm, int pn, int t) const { return t < 256 ? rsqrtf(sum16(px + (size_t)(pm * 256 + t) * 16) * (1.f / 1024.f) + EPS) : bias[pn * 256 + t - 256]; }
;     __device__ __forceinline__ void a_ready(const pg8::Unit& u, int ui) const {
;         if (F::USE_TAB) { const int t = wv * 64 + lane_id_asm(); ((LAS float*)(lds + LDS_TAB))[(ui & 1) * 512 + t] = f.table_val(u.pm, u.pn, t); } }
;     __device__ __forceinline__ float table_val(int pm, int, int t) const { return t < 256 ? rsqrtf(sum16(px + (size_t)(pm * 256 + t) * 16) * (1.f / 1024.f) + EPS) : 0.f; }
.LBB0_1237:
	s_cmp_eq_u32 s77, 10
	s_cbranch_scc0 .Lff1hook_nopf
	s_and_b64 vcc, exec, s[36:37]
	s_cbranch_vccz .Lff1hook_nopf
	v_mbcnt_lo_u32_b32 v140, -1, 0
	v_mbcnt_hi_u32_b32 v140, -1, v140
	v_add_u32_e32 v140, s87, v140
	v_cmp_gt_i32_e32 vcc, s10, v140
	s_and_saveexec_b64 s[60:61], vcc
	s_cbranch_execz .Lff1hook_pfdone
	v_add_u32_e32 v142, s43, v140
	v_ashrrev_i32_e32 v143, 31, v142
	v_lshlrev_b64 v[142:143], 6, v[142:143]
	v_lshl_add_u64 v[154:155], s[94:95], 0, v[142:143]
	global_load_dwordx4 v[216:219], v[154:155], off
	global_load_dwordx4 v[220:223], v[154:155], off offset:16
	global_load_dwordx4 v[224:227], v[154:155], off offset:32
	global_load_dwordx4 v[228:231], v[154:155], off offset:48

; __device__ __forceinline__ float hsum4(f32x4 v) { return (v[0] + v[1]) + (v[2] + v[3]); }
;     __device__ __forceinline__ float table_val(int pm, int, int t) const { return t < 256 ? rsqrtf(sum16(px + (size_t)(pm * 256 + t) * 16) * (1.f / 1024.f) + EPS) : 0.f; }
;     __device__ __forceinline__ float table_val(int pm, int pn, int t) const { return t < 256 ? rsqrtf(sum16(px + (size_t)(pm * 256 + t) * 16) * (1.f / 1024.f) + EPS) : bias[pn * 256 + t - 256]; }
; __device__ __forceinline__ float sum16(const float* p) { const f32x4* q = (const f32x4*)p; return hsum4((q[0] + q[1]) + (q[2] + q[3])); }
;     __device__ __forceinline__ float table_val(int pm, int, int t) const { return t < 256 ? rsqrtf(sum16(px + (size_t)(pm * 256 + t) * 16) * (1.f / 1024.f) + EPS) : 0.f; }
.Lff1hook_nopf:
	s_cmp_eq_u32 s77, 12
	s_cselect_b64 s[58:59], -1, 0
	s_and_b64 s[60:61], s[36:37], s[58:59]
	s_andn2_b64 vcc, exec, s[60:61]
	s_cbranch_vccnz .LBB0_1236
	v_mbcnt_lo_u32_b32 v140, -1, 0
	v_mbcnt_hi_u32_b32 v140, -1, v140
	v_mov_b32_e32 v141, 0
	v_add_u32_e32 v140, s87, v140
	v_cmp_gt_i32_e32 vcc, s10, v140
	s_and_saveexec_b64 s[60:61], vcc
	s_cbranch_execz .LBB0_1235
	s_waitcnt vmcnt(8)
	v_pk_add_f32 v[144:145], v[218:219], v[222:223]
	v_pk_add_f32 v[142:143], v[216:217], v[220:221]
	v_pk_add_f32 v[146:147], v[226:227], v[230:231]
	v_pk_add_f32 v[148:149], v[224:225], v[228:229]
	v_pk_add_f32 v[144:145], v[144:145], v[146:147]
	v_pk_add_f32 v[142:143], v[142:143], v[148:149]
	s_nop 0
	v_pk_mov_b32 v[146:147], v[142:143], v[144:145] op_sel:[1,0]
	v_mov_b32_e32 v143, v145
	v_pk_add_f32 v[142:143], v[146:147], v[142:143]
	s_nop 0
	v_add_f32_e32 v141, v142, v143
	v_fmamk_f32 v141, v141, 0x3a800000, v248
	v_mul_f32_e32 v142, 0x4b800000, v141
	v_cmp_gt_f32_e32 vcc, s48, v141
	s_nop 1
	v_cndmask_b32_e32 v141, v141, v142, vcc
	v_rsq_f32_e32 v141, v141
	s_nop 0
	v_mul_f32_e32 v142, 0x45800000, v141
	v_cndmask_b32_e32 v141, v141, v142, vcc
	s_branch .LBB0_1235
